# v29: v26 + one static s_setprio 1 for waves 0-3 around the latent attention K/V loop
# speedup vs baseline: 1.0053x; 1.0002x over previous
.LBB0_747:
	s_and_b64 vcc, exec, s[10:11]
	s_cbranch_vccz .LBB0_751
	v_mov_b32_e32 v10, v232
	s_load_dwordx8 s[52:59], s[44:45], 0x60
	v_and_b32_e32 v181, 63, v10
	v_readlane_b32 s10, v255, 20
	v_mov_b32_e32 v3, v0
	s_load_dwordx2 s[42:43], s[44:45], 0xb0
	v_or_b32_e32 v2, s10, v181
	v_lshlrev_b64 v[2:3], 2, v[2:3]
	s_waitcnt lgkmcnt(0)
	v_lshl_add_u64 v[4:5], s[52:53], 0, v[2:3]
	global_load_dword v11, v[4:5], off
	v_lshl_add_u64 v[4:5], s[54:55], 0, v[2:3]
	global_load_dword v12, v[4:5], off
	v_lshl_add_u64 v[4:5], s[56:57], 0, v[2:3]
	v_lshl_add_u64 v[2:3], s[58:59], 0, v[2:3]
	global_load_dword v13, v[4:5], off
	global_load_dword v14, v[2:3], off
	s_add_i32 s6, s37, s48
	s_lshl_b32 s14, s36, 7
	s_lshl_b32 s30, s36, 8
	v_readlane_b32 s11, v255, 21
	s_add_u32 s10, s42, s47
	s_addc_u32 s11, s43, s46
	s_add_u32 s36, s10, s30
	s_addc_u32 s37, s11, 0
	s_lshl_b32 s10, s27, 10
	s_or_b32 s10, s14, s10
	s_mul_hi_i32 s11, s10, 0x2200
	s_mulk_i32 s10, 0x2200
	v_ashrrev_i32_e32 v50, 4, v10
	s_add_u32 s10, s42, s10
	v_ashrrev_i32_e32 v51, 31, v50
	v_and_b32_e32 v177, 15, v10
	s_addc_u32 s11, s43, s11
	v_lshlrev_b64 v[52:53], 11, v[50:51]
	s_add_u32 s40, s10, 0xe010000
	v_lshl_add_u64 v[2:3], s[36:37], 0, v[52:53]
	v_lshlrev_b32_e32 v124, 4, v177
	v_mov_b32_e32 v125, v0
	s_addc_u32 s41, s11, 0
	v_lshl_add_u64 v[2:3], v[2:3], 0, v[124:125]
	s_mov_b32 s15, 0x16810000
	v_mov_b64_e32 v[4:5], s[40:41]
	s_movk_i32 s35, 0x2200
	v_add_co_u32_e32 v6, vcc, s15, v2
	v_mad_i64_i32 v[4:5], s[36:37], v50, s35, v[4:5]
	s_nop 0
	v_addc_co_u32_e32 v7, vcc, 0, v3, vcc
	s_mov_b32 s15, 0x16820000
	v_lshl_add_u64 v[4:5], v[4:5], 0, v[124:125]
	global_load_dwordx4 v[18:21], v[6:7], off
	global_load_dwordx4 v[22:25], v[4:5], off
	v_add_co_u32_e32 v6, vcc, s15, v2
	s_mov_b32 s15, 0x44000
	s_nop 0
	v_addc_co_u32_e32 v7, vcc, 0, v3, vcc
	v_add_co_u32_e32 v8, vcc, s15, v4
	s_mov_b32 s15, 0x16830000
	s_nop 0
	v_addc_co_u32_e32 v9, vcc, 0, v5, vcc
	global_load_dwordx4 v[26:29], v[6:7], off
	global_load_dwordx4 v[30:33], v[8:9], off
	v_add_co_u32_e32 v6, vcc, s15, v2
	s_mov_b32 s15, 0x88000
	s_nop 0
	v_addc_co_u32_e32 v7, vcc, 0, v3, vcc
	v_add_co_u32_e32 v8, vcc, s15, v4
	s_mov_b32 s15, 0x16840000
	s_nop 0
	v_addc_co_u32_e32 v9, vcc, 0, v5, vcc
	v_add_co_u32_e32 v2, vcc, s15, v2
	s_mov_b32 s15, 0xcc000
	s_nop 0
	v_addc_co_u32_e32 v3, vcc, 0, v3, vcc
	v_add_co_u32_e32 v4, vcc, s15, v4
	global_load_dwordx4 v[34:37], v[6:7], off
	global_load_dwordx4 v[38:41], v[8:9], off
	v_addc_co_u32_e32 v5, vcc, 0, v5, vcc
	global_load_dwordx4 v[42:45], v[2:3], off
	global_load_dwordx4 v[46:49], v[4:5], off
	v_ashrrev_i32_e32 v4, 2, v10
	v_and_b32_e32 v4, 0xffffffe0, v4
	v_add_u32_e32 v180, s6, v4
	v_ashrrev_i32_e32 v182, 6, v10
	v_and_b32_e32 v179, 1, v182
	v_mov_b32_e32 v55, v0
	v_lshlrev_b32_e32 v54, 7, v179
	s_waitcnt vmcnt(10)
	v_mul_f32_e32 v2, v11, v12
	ds_bpermute_b32 v2, v1, v2
	v_and_b32_e32 v56, 48, v10
	v_mov_b32_e32 v57, v0
	s_waitcnt vmcnt(8)
	v_mul_f32_e32 v3, v13, v14
	ds_bpermute_b32 v3, v1, v3
	s_waitcnt lgkmcnt(1)
	v_fmac_f32_e32 v2, v11, v12
	ds_bpermute_b32 v5, v176, v2
	s_mov_b32 s6, 0x14610000
	s_mov_b64 s[36:37], 0x14610000
	s_waitcnt lgkmcnt(1)
	v_fmac_f32_e32 v3, v13, v14
	ds_bpermute_b32 v6, v176, v3
	s_waitcnt lgkmcnt(1)
	v_add_f32_e32 v4, v2, v5
	v_or_b32_e32 v2, v180, v177
	v_bfe_u32 v178, v10, 4, 2
	v_lshlrev_b32_e32 v51, 2, v50
	s_waitcnt lgkmcnt(0)
	v_add_f32_e32 v5, v3, v6
	ds_bpermute_b32 v6, v175, v4
	ds_bpermute_b32 v7, v175, v5
	v_ashrrev_i32_e32 v3, 31, v2
	v_lshlrev_b64 v[2:3], 11, v[2:3]
	v_lshl_add_u64 v[2:3], s[42:43], 0, v[2:3]
	s_waitcnt lgkmcnt(1)
	v_add_f32_e32 v4, v4, v6
	s_waitcnt lgkmcnt(0)
	v_add_f32_e32 v5, v5, v7
	ds_bpermute_b32 v6, v174, v4
	ds_bpermute_b32 v7, v174, v5
	v_lshl_add_u64 v[2:3], v[2:3], 0, s[30:31]
	v_lshl_add_u64 v[2:3], v[2:3], 0, v[54:55]
	v_lshrrev_b32_e32 v55, 1, v50
	s_waitcnt lgkmcnt(1)
	v_add_f32_e32 v132, v4, v6
	s_waitcnt lgkmcnt(0)
	v_add_f32_e32 v133, v5, v7
	v_lshl_add_u64 v[6:7], v[2:3], 0, v[56:57]
	v_add_co_u32_e32 v4, vcc, s6, v6
	s_mov_b32 s6, 0x14618000
	s_nop 0
	v_addc_co_u32_e32 v5, vcc, 0, v7, vcc
	v_lshl_add_u64 v[2:3], v[6:7], 0, s[36:37]
	v_add_co_u32_e32 v6, vcc, s6, v6
	global_load_dwordx4 v[10:13], v[4:5], off
	s_nop 0
	global_load_dwordx4 v[2:5], v[2:3], off offset:64
	v_addc_co_u32_e32 v7, vcc, 0, v7, vcc
	global_load_dwordx4 v[14:17], v[6:7], off
	s_nop 0
	global_load_dwordx4 v[6:9], v[6:7], off offset:64
	v_and_b32_e32 v51, 16, v51
	v_and_b32_e32 v55, 12, v55
	v_and_b32_e32 v57, 0xfffffe3, v50
	v_or3_b32 v51, v57, v51, v55
	s_movk_i32 s6, 0x110
	v_mul_lo_u32 v55, v50, s6
	v_mad_u64_u32 v[126:127], s[36:37], v51, s6, v[124:125]
	s_mov_b32 s6, 0x11000
	v_add3_u32 v127, v55, v124, s6
	v_add_u32_e32 v51, 0, v126
	v_add_u32_e32 v55, 0, v127
	s_waitcnt vmcnt(11)
	ds_write_b128 v51, v[18:21]
	s_waitcnt vmcnt(10)
	ds_write_b128 v55, v[22:25]
	s_waitcnt vmcnt(9)
	ds_write_b128 v51, v[26:29] offset:8704
	s_waitcnt vmcnt(8)
	ds_write_b128 v55, v[30:33] offset:8704
	s_waitcnt vmcnt(7)
	ds_write_b128 v51, v[34:37] offset:17408
	s_waitcnt vmcnt(6)
	ds_write_b128 v55, v[38:41] offset:17408
	s_waitcnt vmcnt(5)
	ds_write_b128 v51, v[42:45] offset:26112
	s_waitcnt vmcnt(4)
	ds_write_b128 v55, v[46:49] offset:26112
	s_add_i32 s6, 0, 0x11000
	v_mul_u32_u24_e32 v19, 0x110, v177
	v_add3_u32 v183, s6, v56, v19
	s_lshl_b32 s6, s26, 3
	s_and_b32 s6, s6, 0x700
	ds_bpermute_b32 v134, v173, v132
	ds_bpermute_b32 v135, v173, v133
	s_add_u32 s6, s42, s6
	v_add_u32_e32 v18, 0, v54
	s_addc_u32 s18, s43, 0
	v_add3_u32 v137, v18, v56, v19
	s_add_u32 s26, s6, s47
	v_mov_b64_e32 v[18:19], s[10:11]
	s_addc_u32 s27, s18, s46
	v_mad_i64_i32 v[130:131], s[10:11], v50, s35, v[18:19]
	v_mov_b32_e32 v18, 0
	s_mov_b32 s15, 0
	v_lshl_add_u64 v[128:129], s[26:27], 0, v[52:53]
	v_mov_b32_e32 v19, v18
	v_mov_b32_e32 v20, v18
	v_mov_b32_e32 v21, v18
	v_mov_b32_e32 v22, v18
	v_mov_b32_e32 v23, v18
	v_mov_b32_e32 v24, v18
	v_mov_b32_e32 v25, v18
	v_mov_b32_e32 v26, v18
	v_mov_b32_e32 v27, v18
	v_mov_b32_e32 v28, v18
	v_mov_b32_e32 v29, v18
	v_mov_b32_e32 v30, v18
	v_mov_b32_e32 v31, v18
	v_mov_b32_e32 v32, v18
	v_mov_b32_e32 v33, v18
	v_mov_b32_e32 v38, v18
	v_mov_b32_e32 v39, v18
	v_mov_b32_e32 v40, v18
	v_mov_b32_e32 v41, v18
	v_mov_b32_e32 v46, v18
	v_mov_b32_e32 v47, v18
	v_mov_b32_e32 v48, v18
	v_mov_b32_e32 v49, v18
	v_mov_b32_e32 v62, v18
	v_mov_b32_e32 v63, v18
	v_mov_b32_e32 v64, v18
	v_mov_b32_e32 v65, v18
	v_mov_b32_e32 v74, v18
	v_mov_b32_e32 v75, v18
	v_mov_b32_e32 v76, v18
	v_mov_b32_e32 v77, v18
	v_mov_b32_e32 v34, v18
	v_mov_b32_e32 v35, v18
	v_mov_b32_e32 v36, v18
	v_mov_b32_e32 v37, v18
	v_mov_b32_e32 v42, v18
	v_mov_b32_e32 v43, v18
	v_mov_b32_e32 v44, v18
	v_mov_b32_e32 v45, v18
	v_mov_b32_e32 v50, v18
	v_mov_b32_e32 v51, v18
	v_mov_b32_e32 v52, v18
	v_mov_b32_e32 v53, v18
	v_mov_b32_e32 v54, v18
	v_mov_b32_e32 v55, v18
	v_mov_b32_e32 v56, v18
	v_mov_b32_e32 v57, v18
	v_mov_b32_e32 v58, v18
	v_mov_b32_e32 v59, v18
	v_mov_b32_e32 v60, v18
	v_mov_b32_e32 v61, v18
	v_mov_b32_e32 v66, v18
	v_mov_b32_e32 v67, v18
	v_mov_b32_e32 v68, v18
	v_mov_b32_e32 v69, v18
	v_mov_b32_e32 v70, v18
	v_mov_b32_e32 v71, v18
	v_mov_b32_e32 v72, v18
	v_mov_b32_e32 v73, v18
	v_mov_b32_e32 v78, v18
	v_mov_b32_e32 v79, v18
	v_mov_b32_e32 v80, v18
	v_mov_b32_e32 v81, v18
	v_mov_b32_e32 v122, v18
	v_mov_b32_e32 v123, v18
	s_mov_b32 s11, 0xe054000
	s_mov_b32 s18, 0x16870000
	s_mov_b32 s26, 0xe098000
	s_mov_b32 s27, 0x16880000
	s_mov_b32 s30, 0xe0dc000
	s_mov_b64 s[36:37], 0x40000
	s_waitcnt lgkmcnt(0)
	s_barrier
	s_waitcnt vmcnt(0) lgkmcnt(0)
	v_writelane_b32 v175, s64, 0
	v_writelane_b32 v175, s65, 1
	v_writelane_b32 v175, s66, 2
	v_writelane_b32 v175, s67, 3
	v_writelane_b32 v175, s68, 4
	v_writelane_b32 v175, s69, 5
	v_writelane_b32 v175, s70, 6
	v_writelane_b32 v175, s71, 7
	v_writelane_b32 v175, s72, 8
	v_writelane_b32 v175, s73, 9
	v_writelane_b32 v175, s74, 10
	v_writelane_b32 v175, s75, 11
	v_writelane_b32 v175, s76, 12
	v_writelane_b32 v175, s77, 13
	v_writelane_b32 v175, s78, 14
	v_writelane_b32 v175, s79, 15
	v_lshl_add_u64 v[138:139], v[128:129], 0, v[124:125]
	v_lshl_add_u64 v[140:141], v[130:131], 0, v[124:125]
	s_nop 1
	v_readfirstlane_b32 s64, v138
	v_readfirstlane_b32 s65, v139
	v_readfirstlane_b32 s72, v140
	v_readfirstlane_b32 s73, v141
	s_nop 3
	v_subrev_u32_e32 v124, s64, v138
	v_subrev_u32_e32 v125, s72, v140
	s_add_u32 s66, s64, s97
	s_addc_u32 s67, s65, 0
	s_add_u32 s68, s64, s18
	s_addc_u32 s69, s65, 0
	s_add_u32 s70, s64, s27
	s_addc_u32 s71, s65, 0
	s_add_u32 s64, s64, s96
	s_addc_u32 s65, s65, 0
	s_add_u32 s74, s72, s11
	s_addc_u32 s75, s73, 0
	s_add_u32 s74, s74, 0x100
	s_addc_u32 s75, s75, 0
	s_add_u32 s76, s72, s26
	s_addc_u32 s77, s73, 0
	s_add_u32 s76, s76, 0x100
	s_addc_u32 s77, s77, 0
	s_add_u32 s78, s72, s30
	s_addc_u32 s79, s73, 0
	s_add_u32 s78, s78, 0x100
	s_addc_u32 s79, s79, 0
	s_add_u32 s72, s72, s91
	s_addc_u32 s73, s73, 0
	s_add_u32 s72, s72, 0x100
	s_addc_u32 s73, s73, 0
	s_mov_b32 s15, 0
	s_nop 4
	v_readfirstlane_b32 s100, v232
	s_nop 3
	s_lshr_b32 s100, s100, 6
	s_cmp_lt_u32 s100, 4
	s_cbranch_scc0 .Lattn_prio_done
	s_setprio 1
